# x-projection GEMM main loop: LDS-DMA destination offsets go to M0 with one scalar add from the per-wave slice offset (8 fewer SALU per iteration in the load segments)
# baseline (speedup 1.0000x reference)
.LBB0_630:
	s_ashr_i32 s85, s84, 31
	s_lshl_b64 s[22:23], s[84:85], 20
	s_cmp_eq_u32 s52, 0
	v_mov_b64_e32 v[0:1], 0x3a0
	s_cselect_b32 s31, s14, s50
	v_cmp_lt_i64_e32 vcc, s[76:77], v[0:1]
	s_cselect_b32 s30, s15, s51
	s_cselect_b32 s38, s8, s14
	s_cselect_b32 s39, s9, s15
	s_add_u32 s76, s31, s22
	s_addc_u32 s77, s30, s23
	s_and_b64 s[22:23], vcc, exec
	s_cselect_b32 s30, s77, s89
	s_cselect_b32 s31, s76, s88
	s_ashr_i32 s83, s82, 31
	s_lshl_b64 s[22:23], s[82:83], 20
	s_add_u32 s86, s38, s22
	s_addc_u32 s87, s39, s23
	s_and_b64 s[22:23], vcc, exec
	s_cselect_b32 s38, s87, s91
	s_cselect_b32 s39, s86, s90
	s_add_u32 s88, s88, 0x80080
	s_addc_u32 s89, s89, 0
	s_add_u32 s41, s90, 0x100
	s_addc_u32 s42, s91, 0
	s_mov_b32 s43, -2
	s_add_u32 s22, s88, 0xfff80080
	s_addc_u32 s23, s89, -1
	s_add_u32 s44, s88, 0xfff80000
	s_addc_u32 s45, s89, -1
	s_cmp_eq_u32 s43, 28
	s_cselect_b32 s23, s30, s23
	s_cselect_b32 s22, s31, s22
	s_cselect_b32 s91, s38, s42
	s_cselect_b32 s90, s39, s41
	ds_read_b128 v[144:147], v222
	ds_read_b128 v[148:151], v222 offset:1024
	ds_read_b128 v[152:155], v222 offset:2048
	ds_read_b128 v[156:159], v222 offset:3072
	ds_read_b128 v[160:163], v223
	ds_read_b128 v[164:167], v223 offset:1024
	ds_read_b128 v[168:171], v223 offset:2048
	ds_read_b128 v[172:175], v223 offset:3072
	s_mov_b32 m0, s92
	ds_read_b128 v[176:179], v143
	ds_read_b128 v[180:183], v143 offset:1024
	ds_read_b128 v[184:187], v143 offset:2048
	ds_read_b128 v[188:191], v143 offset:3072
	ds_read_b128 v[192:195], v143 offset:4096
	ds_read_b128 v[196:199], v143 offset:5120
	ds_read_b128 v[200:203], v143 offset:6144
	ds_read_b128 v[204:207], v143 offset:7168
	global_load_lds_dwordx4 v128, s[44:45]
	s_mov_b32 m0, s6
	s_nop 0
	global_load_lds_dwordx4 v132, s[44:45]
	s_add_i32 m0, s57, 0xc000
	s_nop 0
	global_load_lds_dwordx4 v136, s[88:89]
	s_add_i32 m0, s57, 0xe000
	s_nop 0
	global_load_lds_dwordx4 v138, s[88:89]
	s_waitcnt vmcnt(8)
	s_waitcnt lgkmcnt(0)
	s_barrier
	v_mfma_f32_16x16x32_bf16 v[124:127], v[144:147], v[176:179], 0
	v_mfma_f32_16x16x32_bf16 v[120:123], v[152:155], v[176:179], 0
	v_mfma_f32_16x16x32_bf16 v[116:119], v[144:147], v[184:187], 0
	v_mfma_f32_16x16x32_bf16 v[112:115], v[152:155], v[184:187], 0
	v_mfma_f32_16x16x32_bf16 v[100:103], v[144:147], v[192:195], 0
	v_mfma_f32_16x16x32_bf16 v[96:99], v[152:155], v[192:195], 0
	v_mfma_f32_16x16x32_bf16 v[84:87], v[144:147], v[200:203], 0
	v_mfma_f32_16x16x32_bf16 v[80:83], v[152:155], v[200:203], 0
	v_mfma_f32_16x16x32_bf16 v[124:127], v[148:151], v[180:183], v[124:127]
	v_mfma_f32_16x16x32_bf16 v[120:123], v[156:159], v[180:183], v[120:123]
	v_mfma_f32_16x16x32_bf16 v[116:119], v[148:151], v[188:191], v[116:119]
	v_mfma_f32_16x16x32_bf16 v[112:115], v[156:159], v[188:191], v[112:115]
	v_mfma_f32_16x16x32_bf16 v[100:103], v[148:151], v[196:199], v[100:103]
	v_mfma_f32_16x16x32_bf16 v[96:99], v[156:159], v[196:199], v[96:99]
	v_mfma_f32_16x16x32_bf16 v[84:87], v[148:151], v[204:207], v[84:87]
	v_mfma_f32_16x16x32_bf16 v[80:83], v[156:159], v[204:207], v[80:83]
	v_mfma_f32_16x16x32_bf16 v[108:111], v[160:163], v[176:179], 0
	v_mfma_f32_16x16x32_bf16 v[104:107], v[168:171], v[176:179], 0
	v_mfma_f32_16x16x32_bf16 v[92:95], v[160:163], v[184:187], 0
	v_mfma_f32_16x16x32_bf16 v[88:91], v[168:171], v[184:187], 0
	v_mfma_f32_16x16x32_bf16 v[76:79], v[160:163], v[192:195], 0
	v_mfma_f32_16x16x32_bf16 v[72:75], v[168:171], v[192:195], 0
	v_mfma_f32_16x16x32_bf16 v[68:71], v[160:163], v[200:203], 0
	v_mfma_f32_16x16x32_bf16 v[64:67], v[168:171], v[200:203], 0
	v_mfma_f32_16x16x32_bf16 v[108:111], v[164:167], v[180:183], v[108:111]
	v_mfma_f32_16x16x32_bf16 v[104:107], v[172:175], v[180:183], v[104:107]
	v_mfma_f32_16x16x32_bf16 v[92:95], v[164:167], v[188:191], v[92:95]
	v_mfma_f32_16x16x32_bf16 v[88:91], v[172:175], v[188:191], v[88:91]
	v_mfma_f32_16x16x32_bf16 v[76:79], v[164:167], v[196:199], v[76:79]
	v_mfma_f32_16x16x32_bf16 v[72:75], v[172:175], v[196:199], v[72:75]
	v_mfma_f32_16x16x32_bf16 v[68:71], v[164:167], v[204:207], v[68:71]
	v_mfma_f32_16x16x32_bf16 v[64:67], v[172:175], v[204:207], v[64:67]
	s_barrier
	s_add_i32 m0, s96, 0x10000
	ds_read_b128 v[176:179], v143 offset:16384
	ds_read_b128 v[180:183], v143 offset:17408
	ds_read_b128 v[184:187], v143 offset:18432
	ds_read_b128 v[188:191], v143 offset:19456
	ds_read_b128 v[192:195], v143 offset:20480
	ds_read_b128 v[196:199], v143 offset:21504
	ds_read_b128 v[200:203], v143 offset:22528
	ds_read_b128 v[204:207], v143 offset:23552
	global_load_lds_dwordx4 v130, s[90:91]
	s_add_i32 m0, s96, 0x12000
	s_add_u32 s44, s90, 0x80000
	s_addc_u32 s45, s91, 0
	global_load_lds_dwordx4 v134, s[90:91]
	s_add_i32 m0, s96, 0x14000
	s_nop 0
	global_load_lds_dwordx4 v130, s[44:45]
	s_add_i32 m0, s96, 0x16000
	s_nop 0
	global_load_lds_dwordx4 v134, s[44:45]
	s_waitcnt vmcnt(6)
	s_waitcnt lgkmcnt(0)
	s_barrier
	v_mfma_f32_16x16x32_bf16 v[60:63], v[144:147], v[176:179], 0
	v_mfma_f32_16x16x32_bf16 v[56:59], v[152:155], v[176:179], 0
	v_mfma_f32_16x16x32_bf16 v[52:55], v[144:147], v[184:187], 0
	v_mfma_f32_16x16x32_bf16 v[48:51], v[152:155], v[184:187], 0
	v_mfma_f32_16x16x32_bf16 v[36:39], v[144:147], v[192:195], 0
	v_mfma_f32_16x16x32_bf16 v[32:35], v[152:155], v[192:195], 0
	v_mfma_f32_16x16x32_bf16 v[20:23], v[144:147], v[200:203], 0
	v_mfma_f32_16x16x32_bf16 v[16:19], v[152:155], v[200:203], 0
	v_mfma_f32_16x16x32_bf16 v[60:63], v[148:151], v[180:183], v[60:63]
	v_mfma_f32_16x16x32_bf16 v[56:59], v[156:159], v[180:183], v[56:59]
	v_mfma_f32_16x16x32_bf16 v[52:55], v[148:151], v[188:191], v[52:55]
	v_mfma_f32_16x16x32_bf16 v[48:51], v[156:159], v[188:191], v[48:51]
	v_mfma_f32_16x16x32_bf16 v[36:39], v[148:151], v[196:199], v[36:39]
	v_mfma_f32_16x16x32_bf16 v[32:35], v[156:159], v[196:199], v[32:35]
	v_mfma_f32_16x16x32_bf16 v[20:23], v[148:151], v[204:207], v[20:23]
	v_mfma_f32_16x16x32_bf16 v[16:19], v[156:159], v[204:207], v[16:19]
	v_mfma_f32_16x16x32_bf16 v[44:47], v[160:163], v[176:179], 0
	v_mfma_f32_16x16x32_bf16 v[40:43], v[168:171], v[176:179], 0
	v_mfma_f32_16x16x32_bf16 v[28:31], v[160:163], v[184:187], 0
	v_mfma_f32_16x16x32_bf16 v[24:27], v[168:171], v[184:187], 0
	v_mfma_f32_16x16x32_bf16 v[12:15], v[160:163], v[192:195], 0
	v_mfma_f32_16x16x32_bf16 v[8:11], v[168:171], v[192:195], 0
	v_mfma_f32_16x16x32_bf16 v[4:7], v[160:163], v[200:203], 0
	v_mfma_f32_16x16x32_bf16 v[0:3], v[168:171], v[200:203], 0
	v_mfma_f32_16x16x32_bf16 v[44:47], v[164:167], v[180:183], v[44:47]
	v_mfma_f32_16x16x32_bf16 v[40:43], v[172:175], v[180:183], v[40:43]
	v_mfma_f32_16x16x32_bf16 v[28:31], v[164:167], v[188:191], v[28:31]
	v_mfma_f32_16x16x32_bf16 v[24:27], v[172:175], v[188:191], v[24:27]
	v_mfma_f32_16x16x32_bf16 v[12:15], v[164:167], v[196:199], v[12:15]
	v_mfma_f32_16x16x32_bf16 v[8:11], v[172:175], v[196:199], v[8:11]
	v_mfma_f32_16x16x32_bf16 v[4:7], v[164:167], v[204:207], v[4:7]
	v_mfma_f32_16x16x32_bf16 v[0:3], v[172:175], v[204:207], v[0:3]
	s_barrier
	ds_read_b128 v[144:147], v224
	ds_read_b128 v[148:151], v224 offset:1024
	ds_read_b128 v[152:155], v224 offset:2048
	ds_read_b128 v[156:159], v224 offset:3072
	ds_read_b128 v[160:163], v225
	ds_read_b128 v[164:167], v225 offset:1024
	ds_read_b128 v[168:171], v225 offset:2048
	ds_read_b128 v[172:175], v225 offset:3072
	ds_read_b128 v[176:179], v143 offset:32768
	ds_read_b128 v[180:183], v143 offset:33792
	ds_read_b128 v[184:187], v143 offset:34816
	ds_read_b128 v[188:191], v143 offset:35840
	ds_read_b128 v[192:195], v143 offset:36864
	ds_read_b128 v[196:199], v143 offset:37888
	ds_read_b128 v[200:203], v143 offset:38912
	ds_read_b128 v[204:207], v143 offset:39936
	s_mov_b32 m0, s57
	s_nop 0
	global_load_lds_dwordx4 v128, s[22:23]
	s_mov_b32 m0, s97
	s_nop 0
	global_load_lds_dwordx4 v132, s[22:23]
	s_mov_b32 m0, s93
	s_add_u32 s22, s22, 0x80000
	s_addc_u32 s23, s23, 0
	global_load_lds_dwordx4 v128, s[22:23]
	s_mov_b32 m0, s94
	s_nop 0
	global_load_lds_dwordx4 v132, s[22:23]
	s_waitcnt vmcnt(8)
	s_waitcnt lgkmcnt(0)
	s_barrier
	v_mfma_f32_16x16x32_bf16 v[124:127], v[144:147], v[176:179], v[124:127]
	v_mfma_f32_16x16x32_bf16 v[120:123], v[152:155], v[176:179], v[120:123]
	v_mfma_f32_16x16x32_bf16 v[116:119], v[144:147], v[184:187], v[116:119]
	v_mfma_f32_16x16x32_bf16 v[112:115], v[152:155], v[184:187], v[112:115]
	v_mfma_f32_16x16x32_bf16 v[100:103], v[144:147], v[192:195], v[100:103]
	v_mfma_f32_16x16x32_bf16 v[96:99], v[152:155], v[192:195], v[96:99]
	v_mfma_f32_16x16x32_bf16 v[84:87], v[144:147], v[200:203], v[84:87]
	v_mfma_f32_16x16x32_bf16 v[80:83], v[152:155], v[200:203], v[80:83]
	v_mfma_f32_16x16x32_bf16 v[124:127], v[148:151], v[180:183], v[124:127]
	v_mfma_f32_16x16x32_bf16 v[120:123], v[156:159], v[180:183], v[120:123]
	v_mfma_f32_16x16x32_bf16 v[116:119], v[148:151], v[188:191], v[116:119]
	v_mfma_f32_16x16x32_bf16 v[112:115], v[156:159], v[188:191], v[112:115]
	v_mfma_f32_16x16x32_bf16 v[100:103], v[148:151], v[196:199], v[100:103]
	v_mfma_f32_16x16x32_bf16 v[96:99], v[156:159], v[196:199], v[96:99]
	v_mfma_f32_16x16x32_bf16 v[84:87], v[148:151], v[204:207], v[84:87]
	v_mfma_f32_16x16x32_bf16 v[80:83], v[156:159], v[204:207], v[80:83]
	v_mfma_f32_16x16x32_bf16 v[108:111], v[160:163], v[176:179], v[108:111]
	v_mfma_f32_16x16x32_bf16 v[104:107], v[168:171], v[176:179], v[104:107]
	v_mfma_f32_16x16x32_bf16 v[92:95], v[160:163], v[184:187], v[92:95]
	v_mfma_f32_16x16x32_bf16 v[88:91], v[168:171], v[184:187], v[88:91]
	v_mfma_f32_16x16x32_bf16 v[76:79], v[160:163], v[192:195], v[76:79]
	v_mfma_f32_16x16x32_bf16 v[72:75], v[168:171], v[192:195], v[72:75]
	v_mfma_f32_16x16x32_bf16 v[68:71], v[160:163], v[200:203], v[68:71]
	v_mfma_f32_16x16x32_bf16 v[64:67], v[168:171], v[200:203], v[64:67]
	v_mfma_f32_16x16x32_bf16 v[108:111], v[164:167], v[180:183], v[108:111]
	v_mfma_f32_16x16x32_bf16 v[104:107], v[172:175], v[180:183], v[104:107]
	v_mfma_f32_16x16x32_bf16 v[92:95], v[164:167], v[188:191], v[92:95]
	v_mfma_f32_16x16x32_bf16 v[88:91], v[172:175], v[188:191], v[88:91]
	v_mfma_f32_16x16x32_bf16 v[76:79], v[164:167], v[196:199], v[76:79]
	v_mfma_f32_16x16x32_bf16 v[72:75], v[172:175], v[196:199], v[72:75]
	v_mfma_f32_16x16x32_bf16 v[68:71], v[164:167], v[204:207], v[68:71]
	v_mfma_f32_16x16x32_bf16 v[64:67], v[172:175], v[204:207], v[64:67]
	s_barrier
	s_add_i32 m0, s96, 0x17f80
	ds_read_b128 v[176:179], v143 offset:49152
	ds_read_b128 v[180:183], v143 offset:50176
	ds_read_b128 v[184:187], v143 offset:51200
	ds_read_b128 v[188:191], v143 offset:52224
	ds_read_b128 v[192:195], v143 offset:53248
	ds_read_b128 v[196:199], v143 offset:54272
	ds_read_b128 v[200:203], v143 offset:55296
	ds_read_b128 v[204:207], v143 offset:56320
	global_load_lds_dwordx4 v130, s[90:91] offset:128
	s_add_i32 m0, s96, 0x19f80
	s_add_u32 s22, s90, 0x80080
	s_addc_u32 s23, s91, 0
	global_load_lds_dwordx4 v134, s[90:91] offset:128
	s_add_i32 m0, s96, 0x1c000
	s_nop 0
	global_load_lds_dwordx4 v130, s[22:23]
	s_add_i32 m0, s96, 0x1e000
	s_nop 0
	global_load_lds_dwordx4 v134, s[22:23]
	s_waitcnt vmcnt(6)
	s_waitcnt lgkmcnt(0)
	s_barrier
	v_mfma_f32_16x16x32_bf16 v[60:63], v[144:147], v[176:179], v[60:63]
	v_mfma_f32_16x16x32_bf16 v[56:59], v[152:155], v[176:179], v[56:59]
	s_add_i32 s43, s43, 2
	v_mfma_f32_16x16x32_bf16 v[52:55], v[144:147], v[184:187], v[52:55]
	s_add_u32 s88, s88, 0x100
	s_addc_u32 s89, s89, 0
	v_mfma_f32_16x16x32_bf16 v[48:51], v[152:155], v[184:187], v[48:51]
	s_add_u32 s41, s41, 0x100
	s_addc_u32 s42, s42, 0
	v_mfma_f32_16x16x32_bf16 v[36:39], v[144:147], v[192:195], v[36:39]
	s_add_u32 s22, s88, 0xfff80080
	s_addc_u32 s23, s89, -1
	v_mfma_f32_16x16x32_bf16 v[32:35], v[152:155], v[192:195], v[32:35]
	s_add_u32 s44, s88, 0xfff80000
	s_addc_u32 s45, s89, -1
	v_mfma_f32_16x16x32_bf16 v[20:23], v[144:147], v[200:203], v[20:23]
	s_cmp_eq_u32 s43, 28
	s_cselect_b32 s23, s30, s23
	s_cselect_b32 s22, s31, s22
	s_cselect_b32 s91, s38, s42
	s_cselect_b32 s90, s39, s41
	v_mfma_f32_16x16x32_bf16 v[16:19], v[152:155], v[200:203], v[16:19]
	v_mfma_f32_16x16x32_bf16 v[60:63], v[148:151], v[180:183], v[60:63]
	v_mfma_f32_16x16x32_bf16 v[56:59], v[156:159], v[180:183], v[56:59]
	v_mfma_f32_16x16x32_bf16 v[52:55], v[148:151], v[188:191], v[52:55]
	v_mfma_f32_16x16x32_bf16 v[48:51], v[156:159], v[188:191], v[48:51]
	v_mfma_f32_16x16x32_bf16 v[36:39], v[148:151], v[196:199], v[36:39]
	v_mfma_f32_16x16x32_bf16 v[32:35], v[156:159], v[196:199], v[32:35]
	v_mfma_f32_16x16x32_bf16 v[20:23], v[148:151], v[204:207], v[20:23]
	v_mfma_f32_16x16x32_bf16 v[16:19], v[156:159], v[204:207], v[16:19]
	v_mfma_f32_16x16x32_bf16 v[44:47], v[160:163], v[176:179], v[44:47]
	v_mfma_f32_16x16x32_bf16 v[40:43], v[168:171], v[176:179], v[40:43]
	v_mfma_f32_16x16x32_bf16 v[28:31], v[160:163], v[184:187], v[28:31]
	v_mfma_f32_16x16x32_bf16 v[24:27], v[168:171], v[184:187], v[24:27]
	v_mfma_f32_16x16x32_bf16 v[12:15], v[160:163], v[192:195], v[12:15]
	v_mfma_f32_16x16x32_bf16 v[8:11], v[168:171], v[192:195], v[8:11]
	v_mfma_f32_16x16x32_bf16 v[4:7], v[160:163], v[200:203], v[4:7]
	v_mfma_f32_16x16x32_bf16 v[0:3], v[168:171], v[200:203], v[0:3]
	v_mfma_f32_16x16x32_bf16 v[44:47], v[164:167], v[180:183], v[44:47]
	v_mfma_f32_16x16x32_bf16 v[40:43], v[172:175], v[180:183], v[40:43]
	v_mfma_f32_16x16x32_bf16 v[28:31], v[164:167], v[188:191], v[28:31]
	v_mfma_f32_16x16x32_bf16 v[24:27], v[172:175], v[188:191], v[24:27]
	v_mfma_f32_16x16x32_bf16 v[12:15], v[164:167], v[196:199], v[12:15]
	v_mfma_f32_16x16x32_bf16 v[8:11], v[172:175], v[196:199], v[8:11]
	v_mfma_f32_16x16x32_bf16 v[4:7], v[164:167], v[204:207], v[4:7]
	v_mfma_f32_16x16x32_bf16 v[0:3], v[172:175], v[204:207], v[0:3]
	s_barrier
	s_cmp_gt_u32 s43, 29
	s_cbranch_scc0 .LBB0_631
.LBB0_631:
	ds_read_b128 v[144:147], v222
	ds_read_b128 v[148:151], v222 offset:1024
	ds_read_b128 v[152:155], v222 offset:2048
	ds_read_b128 v[156:159], v222 offset:3072
	ds_read_b128 v[160:163], v223
	ds_read_b128 v[164:167], v223 offset:1024
	ds_read_b128 v[168:171], v223 offset:2048
	ds_read_b128 v[172:175], v223 offset:3072
	s_mov_b32 m0, s92
	ds_read_b128 v[176:179], v143
	ds_read_b128 v[180:183], v143 offset:1024
	ds_read_b128 v[184:187], v143 offset:2048
	ds_read_b128 v[188:191], v143 offset:3072
	ds_read_b128 v[192:195], v143 offset:4096
	ds_read_b128 v[196:199], v143 offset:5120
	ds_read_b128 v[200:203], v143 offset:6144
	ds_read_b128 v[204:207], v143 offset:7168
	global_load_lds_dwordx4 v128, s[44:45]
	s_mov_b32 m0, s6
	s_nop 0
	global_load_lds_dwordx4 v132, s[44:45]
	s_add_i32 m0, s57, 0xc000
	s_nop 0
	global_load_lds_dwordx4 v136, s[88:89]
	s_add_i32 m0, s57, 0xe000
	s_nop 0
	global_load_lds_dwordx4 v138, s[88:89]
	s_waitcnt vmcnt(8)
	s_waitcnt lgkmcnt(0)
	s_barrier
	v_mfma_f32_16x16x32_bf16 v[124:127], v[144:147], v[176:179], v[124:127]
	v_mfma_f32_16x16x32_bf16 v[120:123], v[152:155], v[176:179], v[120:123]
	v_mfma_f32_16x16x32_bf16 v[116:119], v[144:147], v[184:187], v[116:119]
	v_mfma_f32_16x16x32_bf16 v[112:115], v[152:155], v[184:187], v[112:115]
	v_mfma_f32_16x16x32_bf16 v[100:103], v[144:147], v[192:195], v[100:103]
	v_mfma_f32_16x16x32_bf16 v[96:99], v[152:155], v[192:195], v[96:99]
	v_mfma_f32_16x16x32_bf16 v[84:87], v[144:147], v[200:203], v[84:87]
	v_mfma_f32_16x16x32_bf16 v[80:83], v[152:155], v[200:203], v[80:83]
	v_mfma_f32_16x16x32_bf16 v[124:127], v[148:151], v[180:183], v[124:127]
	v_mfma_f32_16x16x32_bf16 v[120:123], v[156:159], v[180:183], v[120:123]
	v_mfma_f32_16x16x32_bf16 v[116:119], v[148:151], v[188:191], v[116:119]
	v_mfma_f32_16x16x32_bf16 v[112:115], v[156:159], v[188:191], v[112:115]
	v_mfma_f32_16x16x32_bf16 v[100:103], v[148:151], v[196:199], v[100:103]
	v_mfma_f32_16x16x32_bf16 v[96:99], v[156:159], v[196:199], v[96:99]
	v_mfma_f32_16x16x32_bf16 v[84:87], v[148:151], v[204:207], v[84:87]
	v_mfma_f32_16x16x32_bf16 v[80:83], v[156:159], v[204:207], v[80:83]
	v_mfma_f32_16x16x32_bf16 v[108:111], v[160:163], v[176:179], v[108:111]
	v_mfma_f32_16x16x32_bf16 v[104:107], v[168:171], v[176:179], v[104:107]
	v_mfma_f32_16x16x32_bf16 v[92:95], v[160:163], v[184:187], v[92:95]
	v_mfma_f32_16x16x32_bf16 v[88:91], v[168:171], v[184:187], v[88:91]
	v_mfma_f32_16x16x32_bf16 v[76:79], v[160:163], v[192:195], v[76:79]
	v_mfma_f32_16x16x32_bf16 v[72:75], v[168:171], v[192:195], v[72:75]
	v_mfma_f32_16x16x32_bf16 v[68:71], v[160:163], v[200:203], v[68:71]
	v_mfma_f32_16x16x32_bf16 v[64:67], v[168:171], v[200:203], v[64:67]
	v_mfma_f32_16x16x32_bf16 v[108:111], v[164:167], v[180:183], v[108:111]
	v_mfma_f32_16x16x32_bf16 v[104:107], v[172:175], v[180:183], v[104:107]
	v_mfma_f32_16x16x32_bf16 v[92:95], v[164:167], v[188:191], v[92:95]
	v_mfma_f32_16x16x32_bf16 v[88:91], v[172:175], v[188:191], v[88:91]
	v_mfma_f32_16x16x32_bf16 v[76:79], v[164:167], v[196:199], v[76:79]
	v_mfma_f32_16x16x32_bf16 v[72:75], v[172:175], v[196:199], v[72:75]
	v_mfma_f32_16x16x32_bf16 v[68:71], v[164:167], v[204:207], v[68:71]
	v_mfma_f32_16x16x32_bf16 v[64:67], v[172:175], v[204:207], v[64:67]
	s_barrier
	s_add_i32 m0, s96, 0x10000
	ds_read_b128 v[176:179], v143 offset:16384
	ds_read_b128 v[180:183], v143 offset:17408
	ds_read_b128 v[184:187], v143 offset:18432
	ds_read_b128 v[188:191], v143 offset:19456
	ds_read_b128 v[192:195], v143 offset:20480
	ds_read_b128 v[196:199], v143 offset:21504
	ds_read_b128 v[200:203], v143 offset:22528
	ds_read_b128 v[204:207], v143 offset:23552
	global_load_lds_dwordx4 v130, s[90:91]
	s_add_i32 m0, s96, 0x12000
	s_add_u32 s44, s90, 0x80000
	s_addc_u32 s45, s91, 0
	global_load_lds_dwordx4 v134, s[90:91]
	s_add_i32 m0, s96, 0x14000
	s_nop 0
	global_load_lds_dwordx4 v130, s[44:45]
	s_add_i32 m0, s96, 0x16000
	s_nop 0
	global_load_lds_dwordx4 v134, s[44:45]
	s_waitcnt vmcnt(6)
	s_waitcnt lgkmcnt(0)
	s_barrier
	v_mfma_f32_16x16x32_bf16 v[60:63], v[144:147], v[176:179], v[60:63]
	v_mfma_f32_16x16x32_bf16 v[56:59], v[152:155], v[176:179], v[56:59]
	v_mfma_f32_16x16x32_bf16 v[52:55], v[144:147], v[184:187], v[52:55]
	v_mfma_f32_16x16x32_bf16 v[48:51], v[152:155], v[184:187], v[48:51]
	v_mfma_f32_16x16x32_bf16 v[36:39], v[144:147], v[192:195], v[36:39]
	v_mfma_f32_16x16x32_bf16 v[32:35], v[152:155], v[192:195], v[32:35]
	v_mfma_f32_16x16x32_bf16 v[20:23], v[144:147], v[200:203], v[20:23]
	v_mfma_f32_16x16x32_bf16 v[16:19], v[152:155], v[200:203], v[16:19]
	v_mfma_f32_16x16x32_bf16 v[60:63], v[148:151], v[180:183], v[60:63]
	v_mfma_f32_16x16x32_bf16 v[56:59], v[156:159], v[180:183], v[56:59]
	v_mfma_f32_16x16x32_bf16 v[52:55], v[148:151], v[188:191], v[52:55]
	v_mfma_f32_16x16x32_bf16 v[48:51], v[156:159], v[188:191], v[48:51]
	v_mfma_f32_16x16x32_bf16 v[36:39], v[148:151], v[196:199], v[36:39]
	v_mfma_f32_16x16x32_bf16 v[32:35], v[156:159], v[196:199], v[32:35]
	v_mfma_f32_16x16x32_bf16 v[20:23], v[148:151], v[204:207], v[20:23]
	v_mfma_f32_16x16x32_bf16 v[16:19], v[156:159], v[204:207], v[16:19]
	v_mfma_f32_16x16x32_bf16 v[44:47], v[160:163], v[176:179], v[44:47]
	v_mfma_f32_16x16x32_bf16 v[40:43], v[168:171], v[176:179], v[40:43]
	v_mfma_f32_16x16x32_bf16 v[28:31], v[160:163], v[184:187], v[28:31]
	v_mfma_f32_16x16x32_bf16 v[24:27], v[168:171], v[184:187], v[24:27]
	v_mfma_f32_16x16x32_bf16 v[12:15], v[160:163], v[192:195], v[12:15]
	v_mfma_f32_16x16x32_bf16 v[8:11], v[168:171], v[192:195], v[8:11]
	v_mfma_f32_16x16x32_bf16 v[4:7], v[160:163], v[200:203], v[4:7]
	v_mfma_f32_16x16x32_bf16 v[0:3], v[168:171], v[200:203], v[0:3]
	v_mfma_f32_16x16x32_bf16 v[44:47], v[164:167], v[180:183], v[44:47]
	v_mfma_f32_16x16x32_bf16 v[40:43], v[172:175], v[180:183], v[40:43]
	v_mfma_f32_16x16x32_bf16 v[28:31], v[164:167], v[188:191], v[28:31]
	v_mfma_f32_16x16x32_bf16 v[24:27], v[172:175], v[188:191], v[24:27]
	v_mfma_f32_16x16x32_bf16 v[12:15], v[164:167], v[196:199], v[12:15]
	v_mfma_f32_16x16x32_bf16 v[8:11], v[172:175], v[196:199], v[8:11]
	v_mfma_f32_16x16x32_bf16 v[4:7], v[164:167], v[204:207], v[4:7]
	v_mfma_f32_16x16x32_bf16 v[0:3], v[172:175], v[204:207], v[0:3]
	s_barrier
	ds_read_b128 v[144:147], v224
	ds_read_b128 v[148:151], v224 offset:1024
	ds_read_b128 v[152:155], v224 offset:2048
	ds_read_b128 v[156:159], v224 offset:3072
	ds_read_b128 v[160:163], v225
	ds_read_b128 v[164:167], v225 offset:1024
	ds_read_b128 v[168:171], v225 offset:2048
	ds_read_b128 v[172:175], v225 offset:3072
	ds_read_b128 v[176:179], v143 offset:32768
	ds_read_b128 v[180:183], v143 offset:33792
	ds_read_b128 v[184:187], v143 offset:34816
	ds_read_b128 v[188:191], v143 offset:35840
	ds_read_b128 v[192:195], v143 offset:36864
	ds_read_b128 v[196:199], v143 offset:37888
	ds_read_b128 v[200:203], v143 offset:38912
	ds_read_b128 v[204:207], v143 offset:39936
	s_mov_b32 m0, s57
	s_nop 0
	global_load_lds_dwordx4 v128, s[22:23]
	s_mov_b32 m0, s97
	s_nop 0
	global_load_lds_dwordx4 v132, s[22:23]
	s_mov_b32 m0, s93
	s_add_u32 s22, s22, 0x80000
	s_addc_u32 s23, s23, 0
	global_load_lds_dwordx4 v128, s[22:23]
	s_mov_b32 m0, s94
	s_nop 0
	global_load_lds_dwordx4 v132, s[22:23]
	s_waitcnt vmcnt(8)
	s_waitcnt lgkmcnt(0)
	s_barrier
	v_mfma_f32_16x16x32_bf16 v[124:127], v[144:147], v[176:179], v[124:127]
	v_mfma_f32_16x16x32_bf16 v[120:123], v[152:155], v[176:179], v[120:123]
	v_mfma_f32_16x16x32_bf16 v[116:119], v[144:147], v[184:187], v[116:119]
	v_mfma_f32_16x16x32_bf16 v[112:115], v[152:155], v[184:187], v[112:115]
	v_mfma_f32_16x16x32_bf16 v[100:103], v[144:147], v[192:195], v[100:103]
	v_mfma_f32_16x16x32_bf16 v[96:99], v[152:155], v[192:195], v[96:99]
	v_mfma_f32_16x16x32_bf16 v[84:87], v[144:147], v[200:203], v[84:87]
	v_mfma_f32_16x16x32_bf16 v[80:83], v[152:155], v[200:203], v[80:83]
	v_mfma_f32_16x16x32_bf16 v[124:127], v[148:151], v[180:183], v[124:127]
	v_mfma_f32_16x16x32_bf16 v[120:123], v[156:159], v[180:183], v[120:123]
	v_mfma_f32_16x16x32_bf16 v[116:119], v[148:151], v[188:191], v[116:119]
	v_mfma_f32_16x16x32_bf16 v[112:115], v[156:159], v[188:191], v[112:115]
	v_mfma_f32_16x16x32_bf16 v[100:103], v[148:151], v[196:199], v[100:103]
	v_mfma_f32_16x16x32_bf16 v[96:99], v[156:159], v[196:199], v[96:99]
	v_mfma_f32_16x16x32_bf16 v[84:87], v[148:151], v[204:207], v[84:87]
	v_mfma_f32_16x16x32_bf16 v[80:83], v[156:159], v[204:207], v[80:83]
	v_mfma_f32_16x16x32_bf16 v[108:111], v[160:163], v[176:179], v[108:111]
	v_mfma_f32_16x16x32_bf16 v[104:107], v[168:171], v[176:179], v[104:107]
	v_mfma_f32_16x16x32_bf16 v[92:95], v[160:163], v[184:187], v[92:95]
	v_mfma_f32_16x16x32_bf16 v[88:91], v[168:171], v[184:187], v[88:91]
	v_mfma_f32_16x16x32_bf16 v[76:79], v[160:163], v[192:195], v[76:79]
	v_mfma_f32_16x16x32_bf16 v[72:75], v[168:171], v[192:195], v[72:75]
	v_mfma_f32_16x16x32_bf16 v[68:71], v[160:163], v[200:203], v[68:71]
	v_mfma_f32_16x16x32_bf16 v[64:67], v[168:171], v[200:203], v[64:67]
	v_mfma_f32_16x16x32_bf16 v[108:111], v[164:167], v[180:183], v[108:111]
	v_mfma_f32_16x16x32_bf16 v[104:107], v[172:175], v[180:183], v[104:107]
	v_mfma_f32_16x16x32_bf16 v[92:95], v[164:167], v[188:191], v[92:95]
	v_mfma_f32_16x16x32_bf16 v[88:91], v[172:175], v[188:191], v[88:91]
	v_mfma_f32_16x16x32_bf16 v[76:79], v[164:167], v[196:199], v[76:79]
	v_mfma_f32_16x16x32_bf16 v[72:75], v[172:175], v[196:199], v[72:75]
	v_mfma_f32_16x16x32_bf16 v[68:71], v[164:167], v[204:207], v[68:71]
	v_mfma_f32_16x16x32_bf16 v[64:67], v[172:175], v[204:207], v[64:67]
	s_barrier
	s_add_i32 m0, s96, 0x17f80
	ds_read_b128 v[176:179], v143 offset:49152
	ds_read_b128 v[180:183], v143 offset:50176
	ds_read_b128 v[184:187], v143 offset:51200
	ds_read_b128 v[188:191], v143 offset:52224
	ds_read_b128 v[192:195], v143 offset:53248
	ds_read_b128 v[196:199], v143 offset:54272
	ds_read_b128 v[200:203], v143 offset:55296
	ds_read_b128 v[204:207], v143 offset:56320
	global_load_lds_dwordx4 v130, s[90:91] offset:128
	s_add_i32 m0, s96, 0x19f80
	s_add_u32 s22, s90, 0x80080
	s_addc_u32 s23, s91, 0
	global_load_lds_dwordx4 v134, s[90:91] offset:128
	s_add_i32 m0, s96, 0x1c000
	s_nop 0
	global_load_lds_dwordx4 v130, s[22:23]
	s_add_i32 m0, s96, 0x1e000
	s_nop 0
	global_load_lds_dwordx4 v134, s[22:23]
	s_waitcnt vmcnt(6)
	s_waitcnt lgkmcnt(0)
	s_barrier
	v_mfma_f32_16x16x32_bf16 v[60:63], v[144:147], v[176:179], v[60:63]
	v_mfma_f32_16x16x32_bf16 v[56:59], v[152:155], v[176:179], v[56:59]
	s_add_i32 s43, s43, 2
	v_mfma_f32_16x16x32_bf16 v[52:55], v[144:147], v[184:187], v[52:55]
	s_add_u32 s88, s88, 0x100
	s_addc_u32 s89, s89, 0
	v_mfma_f32_16x16x32_bf16 v[48:51], v[152:155], v[184:187], v[48:51]
	s_add_u32 s41, s41, 0x100
	s_addc_u32 s42, s42, 0
	v_mfma_f32_16x16x32_bf16 v[36:39], v[144:147], v[192:195], v[36:39]
	s_add_u32 s22, s88, 0xfff80080
	s_addc_u32 s23, s89, -1
	v_mfma_f32_16x16x32_bf16 v[32:35], v[152:155], v[192:195], v[32:35]
	s_add_u32 s44, s88, 0xfff80000
	s_addc_u32 s45, s89, -1
	v_mfma_f32_16x16x32_bf16 v[20:23], v[144:147], v[200:203], v[20:23]
	s_cmp_eq_u32 s43, 28
	s_cselect_b32 s23, s30, s23
	s_cselect_b32 s22, s31, s22
	s_cselect_b32 s91, s38, s42
	s_cselect_b32 s90, s39, s41
	v_mfma_f32_16x16x32_bf16 v[16:19], v[152:155], v[200:203], v[16:19]
	v_mfma_f32_16x16x32_bf16 v[60:63], v[148:151], v[180:183], v[60:63]
	v_mfma_f32_16x16x32_bf16 v[56:59], v[156:159], v[180:183], v[56:59]
	v_mfma_f32_16x16x32_bf16 v[52:55], v[148:151], v[188:191], v[52:55]
	v_mfma_f32_16x16x32_bf16 v[48:51], v[156:159], v[188:191], v[48:51]
	v_mfma_f32_16x16x32_bf16 v[36:39], v[148:151], v[196:199], v[36:39]
	v_mfma_f32_16x16x32_bf16 v[32:35], v[156:159], v[196:199], v[32:35]
	v_mfma_f32_16x16x32_bf16 v[20:23], v[148:151], v[204:207], v[20:23]
	v_mfma_f32_16x16x32_bf16 v[16:19], v[156:159], v[204:207], v[16:19]
	v_mfma_f32_16x16x32_bf16 v[44:47], v[160:163], v[176:179], v[44:47]
	v_mfma_f32_16x16x32_bf16 v[40:43], v[168:171], v[176:179], v[40:43]
	v_mfma_f32_16x16x32_bf16 v[28:31], v[160:163], v[184:187], v[28:31]
	v_mfma_f32_16x16x32_bf16 v[24:27], v[168:171], v[184:187], v[24:27]
	v_mfma_f32_16x16x32_bf16 v[12:15], v[160:163], v[192:195], v[12:15]
	v_mfma_f32_16x16x32_bf16 v[8:11], v[168:171], v[192:195], v[8:11]
	v_mfma_f32_16x16x32_bf16 v[4:7], v[160:163], v[200:203], v[4:7]
	v_mfma_f32_16x16x32_bf16 v[0:3], v[168:171], v[200:203], v[0:3]
	v_mfma_f32_16x16x32_bf16 v[44:47], v[164:167], v[180:183], v[44:47]
	v_mfma_f32_16x16x32_bf16 v[40:43], v[172:175], v[180:183], v[40:43]
	v_mfma_f32_16x16x32_bf16 v[28:31], v[164:167], v[188:191], v[28:31]
	v_mfma_f32_16x16x32_bf16 v[24:27], v[172:175], v[188:191], v[24:27]
	v_mfma_f32_16x16x32_bf16 v[12:15], v[164:167], v[196:199], v[12:15]
	v_mfma_f32_16x16x32_bf16 v[8:11], v[172:175], v[196:199], v[8:11]
	v_mfma_f32_16x16x32_bf16 v[4:7], v[164:167], v[204:207], v[4:7]
	v_mfma_f32_16x16x32_bf16 v[0:3], v[172:175], v[204:207], v[0:3]
	s_barrier
	s_cmp_gt_u32 s43, 29
	s_cbranch_scc0 .LBB0_631
	s_cmp_eq_u32 s40, 0
	s_cselect_b64 s[30:31], -1, 0
	s_cmp_lg_u32 s40, 0
	s_mov_b64 s[38:39], -1
	s_cbranch_scc0 .LBB0_634
	s_lshl_b32 s22, s80, 8
	s_or_b32 s22, s22, s53
	s_ashr_i32 s22, s22, 6
	s_mov_b64 s[38:39], 0
